# window loop: relax vmcnt(0) before QK to vmcnt(2) so next-tile prefetch stays in flight; moba gather: counted vmcnt so next-item KV prefetch overlaps compute
# baseline (speedup 1.0000x reference)
; DI float bflo(uint32_t w) { return __uint_as_float(w << 16); }
; DI float bfhi(uint32_t w) { return __uint_as_float(w & 0xffff0000u); }
; DI float fexp2(float x) { return __builtin_amdgcn_exp2f(x); }
; template <int MODE>
; DI void osm(f32x16* s, uint32_t vm, float& m, float& l, f32x16* o) {
;   float mx = -1e30f;
; #pragma unroll
;   for (int kb = 0; kb < 2; ++kb)
; #pragma unroll
;     for (int i = 0; i < 16; ++i) {
;       if (MODE == 2) s[kb][i] = ((vm >> (kb * 16 + i)) & 1u) ? s[kb][i] : -1e30f;
;       mx = fmaxf(mx, s[kb][i]);
;     }
;   mx *= SCL2;
;   if (MODE == 1) mx = vm ? mx : -1e30f;
;   mx = xmax32(mx);
;   const float mn = fmaxf(m, mx);
;   const float alpha = fexp2(m - mn);
;   const bool rowok = (MODE == 1) ? (vm != 0u) : true;
;   const float mu = (rowok && mn > -1e29f) ? mn : 1e30f;
;   float rs = 0.f;
; #pragma unroll
;   for (int kb = 0; kb < 2; ++kb)
; #pragma unroll
;     for (int i = 0; i < 16; ++i) {
;       const float pv = fexp2(__builtin_fmaf(s[kb][i], SCL2, -mu));
;       s[kb][i] = pv;
;       rs += pv;
;     }
;   rs = xsum32(rs);
;   l = l * alpha + rs;
;   if (__ballot(mn > m) != 0ull) {
; #pragma unroll
;     for (int db = 0; db < 2; ++db)
; #pragma unroll
;       for (int i = 0; i < 16; ++i) o[db][i] *= alpha;
;   }
;   m = mn;
; }
; DI bf16x8 rope_frag(bf16x8 f, const float* cs  , int hh) {
;   u32x4 w = __builtin_bit_cast(u32x4, f), ow;
; #pragma unroll
;   for (int q = 0; q < 4; ++q) ow[q] = shxi<32>((int)w[q]);
;   float mine[8], oth[8], res[8];
; #pragma unroll
;   for (int q = 0; q < 4; ++q) {
;     mine[2 * q] = bflo(w[q]); mine[2 * q + 1] = bfhi(w[q]);
;     oth[2 * q] = bflo(ow[q]); oth[2 * q + 1] = bfhi(ow[q]);
;   }
;   const float sg = hh ? 1.f : -1.f;
; #pragma unroll
;   for (int i = 0; i < 8; ++i) res[i] = mine[i] * cs[i] + sg * oth[i] * cs[8 + i];
;   u32x4 r = {pack2(res[0], res[1]), pack2(res[2], res[3]), pack2(res[4], res[5]), pack2(res[6], res[7])};
;   return __builtin_bit_cast(bf16x8, r);
; }
.LBB0_743:
	s_mov_b64 s[44:45], 0
	v_mov_b32_e32 v151, 0
	s_mov_b32 s34, 0
	s_waitcnt vmcnt(0)
.LBB0_744:
	v_xor_b32_e32 v20, v21, v20
	v_xor_b32_sdwa v28, v20, v0 dst_sel:WORD_1 dst_unused:UNUSED_PAD src0_sel:DWORD src1_sel:DWORD
	v_xor_b32_e32 v21, v23, v22
	v_xor_b32_e32 v22, v25, v24
	v_xor_b32_e32 v23, v27, v26
	v_bitop3_b32 v26, v20, s3, v0 bitop3:0x48
	v_xor_b32_sdwa v24, v22, v2 dst_sel:WORD_1 dst_unused:UNUSED_PAD src0_sel:DWORD src1_sel:DWORD
	v_xor_b32_sdwa v25, v23, v3 dst_sel:WORD_1 dst_unused:UNUSED_PAD src0_sel:DWORD src1_sel:DWORD
	v_bitop3_b32 v30, v22, s3, v2 bitop3:0x48
	v_bitop3_b32 v31, v23, s3, v3 bitop3:0x48
	v_cndmask_b32_e64 v23, v26, -v26, s[10:11]
	v_cndmask_b32_e64 v22, v28, -v28, s[10:11]
	v_xor_b32_sdwa v29, v21, v1 dst_sel:WORD_1 dst_unused:UNUSED_PAD src0_sel:DWORD src1_sel:DWORD
	v_bitop3_b32 v27, v21, s3, v1 bitop3:0x48
	v_lshlrev_b32_e32 v20, 16, v0
	v_and_b32_e32 v21, 0xffff0000, v0
	s_waitcnt vmcnt(9)
	v_pk_mul_f32 v[12:13], v[12:13], v[22:23]
	v_lshlrev_b32_e32 v0, 16, v1
	s_waitcnt vmcnt(9)
	v_pk_fma_f32 v[12:13], v[16:17], v[20:21], v[12:13]
	v_cndmask_b32_e64 v17, v27, -v27, s[10:11]
	v_cndmask_b32_e64 v16, v29, -v29, s[10:11]
	v_and_b32_e32 v1, 0xffff0000, v1
	v_pk_mul_f32 v[14:15], v[16:17], v[14:15]
	v_cndmask_b32_e64 v17, v30, -v30, s[10:11]
	v_cndmask_b32_e64 v16, v24, -v24, s[10:11]
	v_pk_fma_f32 v[14:15], v[18:19], v[0:1], v[14:15]
	v_lshlrev_b32_e32 v0, 16, v2
	v_and_b32_e32 v1, 0xffff0000, v2
	v_pk_mul_f32 v[4:5], v[16:17], v[4:5]
	v_cndmask_b32_e64 v17, v31, -v31, s[10:11]
	v_pk_fma_f32 v[4:5], v[8:9], v[0:1], v[4:5]
	v_lshlrev_b32_e32 v8, 16, v3
	v_and_b32_e32 v9, 0xffff0000, v3
	ds_read_b128 v[0:3], v149
	v_cndmask_b32_e64 v16, v25, -v25, s[10:11]
	v_pk_mul_f32 v[6:7], v[16:17], v[6:7]
	v_cvt_pk_bf16_f32 v124, v12, v13
	v_pk_fma_f32 v[6:7], v[10:11], v[8:9], v[6:7]
	v_cvt_pk_bf16_f32 v125, v14, v15
	v_cvt_pk_bf16_f32 v126, v4, v5
	v_cvt_pk_bf16_f32 v127, v6, v7
	ds_read_b128 v[16:19], v149 offset:32
	v_add_u32_e32 v63, 0x2000, v161
	s_waitcnt lgkmcnt(1)
	v_mfma_f32_32x32x16_bf16 v[0:15], v[0:3], v[124:127], 0
	v_add_u32_e32 v176, 0x3000, v161
	s_waitcnt lgkmcnt(0)
	v_mfma_f32_32x32x16_bf16 v[0:15], v[16:19], v[120:123], v[0:15]
	ds_read_b128 v[16:19], v149 offset:64
	ds_read_b128 v[20:23], v149 offset:96
	s_waitcnt lgkmcnt(1)
	v_mfma_f32_32x32x16_bf16 v[0:15], v[16:19], v[116:119], v[0:15]
	s_waitcnt lgkmcnt(0)
	v_mfma_f32_32x32x16_bf16 v[0:15], v[20:23], v[112:115], v[0:15]
	ds_read_b128 v[16:19], v149 offset:4608
	ds_read_b128 v[20:23], v149 offset:4640
	s_waitcnt lgkmcnt(1)
	v_mfma_f32_32x32x16_bf16 v[30:45], v[16:19], v[124:127], 0
	s_waitcnt lgkmcnt(0)
	v_mfma_f32_32x32x16_bf16 v[30:45], v[20:23], v[120:123], v[30:45]
	ds_read_b128 v[16:19], v149 offset:4672
	ds_read_b128 v[20:23], v149 offset:4704
	s_waitcnt lgkmcnt(1)
	v_mfma_f32_32x32x16_bf16 v[30:45], v[16:19], v[116:119], v[30:45]
	s_nop 1
	v_max3_f32 v16, v0, s6, v1
	v_max3_f32 v16, v16, v2, v3
	v_max3_f32 v16, v16, v4, v5
	v_max3_f32 v16, v16, v6, v7
	v_max3_f32 v16, v16, v8, v9
	v_max3_f32 v16, v16, v10, v11
	v_max3_f32 v16, v16, v12, v13
	s_waitcnt lgkmcnt(0)
	v_mfma_f32_32x32x16_bf16 v[30:45], v[20:23], v[112:115], v[30:45]
	v_max3_f32 v16, v16, v14, v15
	s_nop 10
	v_max3_f32 v16, v16, v30, v31
	v_max3_f32 v16, v16, v32, v33
	v_max3_f32 v16, v16, v34, v35
	v_max3_f32 v16, v16, v36, v37
	v_max3_f32 v16, v16, v38, v39
	v_max3_f32 v16, v16, v40, v41
	v_max3_f32 v16, v16, v42, v43
	v_max3_f32 v16, v16, v44, v45
	v_mul_f32_e32 v16, 0x3e38aa3b, v16
	v_mov_b32_e32 v17, v16
	s_nop 1
	v_permlane32_swap_b32_e32 v16, v17
	v_max3_f32 v155, v16, v17, s6
	v_cmp_lt_f32_e32 vcc, s7, v155
	v_sub_f32_e32 v16, 0xf149f2ca, v155
	s_nop 0
	v_cndmask_b32_e64 v62, v163, -v155, vcc
	v_fmamk_f32 v0, v0, 0x3e38aa3b, v62
	v_exp_f32_e32 v128, v0
	v_fmamk_f32 v0, v1, 0x3e38aa3b, v62
	v_exp_f32_e32 v129, v0
	v_fmamk_f32 v0, v2, 0x3e38aa3b, v62
	v_exp_f32_e32 v130, v0
	v_fmamk_f32 v0, v3, 0x3e38aa3b, v62
	v_exp_f32_e32 v131, v0
	v_fmamk_f32 v0, v4, 0x3e38aa3b, v62
	v_exp_f32_e32 v132, v0
	v_fmamk_f32 v0, v5, 0x3e38aa3b, v62
	v_exp_f32_e32 v133, v0
	v_fmamk_f32 v0, v6, 0x3e38aa3b, v62
	v_exp_f32_e32 v134, v0
	v_fmamk_f32 v0, v7, 0x3e38aa3b, v62
	v_exp_f32_e32 v135, v0
	v_fmamk_f32 v0, v8, 0x3e38aa3b, v62
	v_exp_f32_e32 v136, v0
	v_fmamk_f32 v0, v9, 0x3e38aa3b, v62
	v_exp_f32_e32 v158, v0
	v_fmamk_f32 v0, v10, 0x3e38aa3b, v62
	v_exp_f32_e32 v168, v0
	v_fmamk_f32 v0, v11, 0x3e38aa3b, v62
	v_exp_f32_e32 v169, v0
	v_fmamk_f32 v0, v12, 0x3e38aa3b, v62
	v_exp_f32_e32 v170, v0
	v_fmamk_f32 v0, v13, 0x3e38aa3b, v62
	v_exp_f32_e32 v171, v0
	v_fmamk_f32 v0, v14, 0x3e38aa3b, v62
	v_exp_f32_e32 v172, v0
	v_fmamk_f32 v0, v15, 0x3e38aa3b, v62
	v_cvt_pk_bf16_f32 v46, v128, v129
	v_cvt_pk_bf16_f32 v47, v130, v131
	v_cvt_pk_bf16_f32 v48, v132, v133
	v_cvt_pk_bf16_f32 v49, v134, v135
	s_nop 1
	ds_read2_b64 v[50:53], v63 offset0:128 offset1:130
	v_exp_f32_e32 v173, v0
	v_fmamk_f32 v0, v30, 0x3e38aa3b, v62
	ds_read2_b64 v[54:57], v176 offset0:192 offset1:194
	v_exp_f32_e32 v174, v0
	v_exp_f32_e32 v0, v16
	v_fmamk_f32 v32, v32, 0x3e38aa3b, v62
	v_cmp_lt_f32_e32 vcc, s6, v155
	v_exp_f32_e32 v177, v32
	v_fmamk_f32 v32, v33, 0x3e38aa3b, v62
	s_cmp_lg_u64 vcc, 0
	v_exp_f32_e32 v178, v32
	v_fmamk_f32 v32, v34, 0x3e38aa3b, v62
	v_mul_f32_e32 v157, 0, v0
	s_cselect_b64 vcc, -1, 0
	v_exp_f32_e32 v179, v32
	v_fmamk_f32 v32, v35, 0x3e38aa3b, v62
	v_fmamk_f32 v1, v31, 0x3e38aa3b, v62
	v_cndmask_b32_e32 v0, 0, v157, vcc
	v_exp_f32_e32 v180, v32
	v_fmamk_f32 v32, v36, 0x3e38aa3b, v62
	v_exp_f32_e32 v175, v1
	v_mov_b32_e32 v1, v0
	v_mov_b32_e32 v2, v0
	v_mov_b32_e32 v3, v0
	v_mov_b32_e32 v4, v0
	v_mov_b32_e32 v5, v0
	v_mov_b32_e32 v6, v0
	v_mov_b32_e32 v7, v0
	v_mov_b32_e32 v8, v0
	v_mov_b32_e32 v9, v0
	v_mov_b32_e32 v10, v0
	v_mov_b32_e32 v11, v0
	v_mov_b32_e32 v12, v0
	v_mov_b32_e32 v13, v0
	v_mov_b32_e32 v14, v0
	v_mov_b32_e32 v15, v0
	v_exp_f32_e32 v181, v32
	v_fmamk_f32 v32, v37, 0x3e38aa3b, v62
	s_waitcnt lgkmcnt(1)
; #define MFMA32(a, b, c) __builtin_amdgcn_mfma_f32_32x32x16_bf16((a), (b), (c), 0, 0, 0)
; DI float fexp2(float x) { return __builtin_amdgcn_exp2f(x); }
; DI void pv_tile(const u16* Vs, const f32x16* s, f32x16* o, int rl, int hh) {
; #pragma unroll
;   for (int kk = 0; kk < 4; ++kk) {
;     const int kb = kk >> 1, i0 = 8 * (kk & 1);
;     bf16x8 pf = pack8(s[kb][i0], s[kb][i0 + 1], s[kb][i0 + 2], s[kb][i0 + 3], s[kb][i0 + 4], s[kb][i0 + 5], s[kb][i0 + 6], s[kb][i0 + 7]);
; #pragma unroll
;     for (int db = 0; db < 2; ++db) {
;       const u16* vp = Vs + (db * 32 + rl) * KVS + kk * 16 + hh * 4;
;       s16x4 lo = *(const s16x4*)vp, hi = *(const s16x4*)(vp + 8);
;       bf16x8 a = __builtin_shufflevector(lo, hi, 0, 1, 2, 3, 4, 5, 6, 7);
;       o[db] = MFMA32(a, pf, o[db]);
;     }
;   }
; }
; template <int MODE>
; DI void osm(f32x16* s, uint32_t vm, float& m, float& l, f32x16* o) {
;   float mx = -1e30f;
; #pragma unroll
;   for (int kb = 0; kb < 2; ++kb)
; #pragma unroll
;     for (int i = 0; i < 16; ++i) {
;       if (MODE == 2) s[kb][i] = ((vm >> (kb * 16 + i)) & 1u) ? s[kb][i] : -1e30f;
;       mx = fmaxf(mx, s[kb][i]);
;     }
;   mx *= SCL2;
;   if (MODE == 1) mx = vm ? mx : -1e30f;
;   mx = xmax32(mx);
;   const float mn = fmaxf(m, mx);
;   const float alpha = fexp2(m - mn);
;   const bool rowok = (MODE == 1) ? (vm != 0u) : true;
;   const float mu = (rowok && mn > -1e29f) ? mn : 1e30f;
;   float rs = 0.f;
; #pragma unroll
;   for (int kb = 0; kb < 2; ++kb)
; #pragma unroll
;     for (int i = 0; i < 16; ++i) {
;       const float pv = fexp2(__builtin_fmaf(s[kb][i], SCL2, -mu));
;       s[kb][i] = pv;
;       rs += pv;
;     }
;   rs = xsum32(rs);
;   l = l * alpha + rs;
;   if (__ballot(mn > m) != 0ull) {
; #pragma unroll
;     for (int db = 0; db < 2; ++db)
; #pragma unroll
;       for (int i = 0; i < 16; ++i) o[db][i] *= alpha;
;   }
;   m = mn;
; }
	v_mfma_f32_32x32x16_bf16 v[16:31], v[50:53], v[46:49], v[0:15]
	v_cvt_pk_bf16_f32 v50, v136, v158
	v_cvt_pk_bf16_f32 v51, v168, v169
	v_cvt_pk_bf16_f32 v52, v170, v171
	v_cvt_pk_bf16_f32 v53, v172, v173
	s_nop 1
	v_exp_f32_e32 v182, v32
	ds_read2_b64 v[32:35], v176 offset0:196 offset1:198
	ds_read2_b64 v[58:61], v63 offset0:132 offset1:134
	v_fmamk_f32 v36, v38, 0x3e38aa3b, v62
	v_exp_f32_e32 v183, v36
	v_fmamk_f32 v36, v39, 0x3e38aa3b, v62
	s_waitcnt lgkmcnt(2)
	v_mfma_f32_32x32x16_bf16 v[0:15], v[54:57], v[46:49], v[0:15]
	v_exp_f32_e32 v184, v36
	v_cvt_pk_bf16_f32 v36, v174, v175
	v_cvt_pk_bf16_f32 v37, v177, v178
	v_cvt_pk_bf16_f32 v38, v179, v180
	v_cvt_pk_bf16_f32 v39, v181, v182
	s_nop 1
	ds_read2_b64 v[46:49], v63 offset0:136 offset1:138
	v_fmamk_f32 v40, v40, 0x3e38aa3b, v62
	v_exp_f32_e32 v185, v40
	v_fmamk_f32 v40, v43, 0x3e38aa3b, v62
	v_exp_f32_e32 v188, v40
	s_waitcnt lgkmcnt(2)
	v_mfma_f32_32x32x16_bf16 v[0:15], v[32:35], v[50:53], v[0:15]
	v_fmamk_f32 v32, v41, 0x3e38aa3b, v62
	v_exp_f32_e32 v186, v32
	v_fmamk_f32 v32, v42, 0x3e38aa3b, v62
	v_exp_f32_e32 v187, v32
	ds_read2_b64 v[32:35], v176 offset0:200 offset1:202
	v_fmamk_f32 v40, v44, 0x3e38aa3b, v62
	v_fmac_f32_e32 v62, 0x3e38aa3b, v45
	s_waitcnt lgkmcnt(2)
	v_mfma_f32_32x32x16_bf16 v[16:31], v[58:61], v[50:53], v[16:31]
	v_exp_f32_e32 v189, v40
	v_exp_f32_e32 v190, v62
	s_waitcnt lgkmcnt(1)
	v_mfma_f32_32x32x16_bf16 v[16:31], v[46:49], v[36:39], v[16:31]
	s_waitcnt lgkmcnt(0)
	v_mfma_f32_32x32x16_bf16 v[0:15], v[32:35], v[36:39], v[0:15]
	v_cvt_pk_bf16_f32 v32, v183, v184
	v_cvt_pk_bf16_f32 v33, v185, v186
	v_cvt_pk_bf16_f32 v34, v187, v188
	v_cvt_pk_bf16_f32 v35, v189, v190
	s_nop 1
	ds_read2_b64 v[36:39], v63 offset0:140 offset1:142
	s_waitcnt lgkmcnt(0)
	v_mfma_f32_32x32x16_bf16 v[16:31], v[36:39], v[32:35], v[16:31]
	ds_read2_b64 v[36:39], v176 offset0:204 offset1:206
	s_waitcnt lgkmcnt(0)
	v_mfma_f32_32x32x16_bf16 v[0:15], v[36:39], v[32:35], v[0:15]
	ds_read_b128 v[32:35], v149 offset:18432
	ds_read_b128 v[36:39], v149 offset:18464
	s_waitcnt lgkmcnt(1)
	v_mfma_f32_32x32x16_bf16 v[48:63], v[32:35], v[124:127], 0
	ds_read_b128 v[32:35], v149 offset:18496
	s_waitcnt lgkmcnt(1)
	v_mfma_f32_32x32x16_bf16 v[48:63], v[36:39], v[120:123], v[48:63]
	v_add_f32_e32 v36, 0, v128
	v_add_f32_e32 v36, v129, v36
	v_add_f32_e32 v36, v130, v36
	v_add_f32_e32 v40, v131, v36
	ds_read_b128 v[36:39], v149 offset:18528
	ds_read_b128 v[128:131], v149 offset:23072
	s_waitcnt lgkmcnt(2)
	v_mfma_f32_32x32x16_bf16 v[48:63], v[32:35], v[116:119], v[48:63]
	v_add_f32_e32 v32, v132, v40
	v_add_f32_e32 v32, v133, v32
	v_add_f32_e32 v32, v134, v32
	v_add_f32_e32 v32, v135, v32
	v_add_f32_e32 v32, v136, v32
	v_add_f32_e32 v40, v158, v32
	ds_read_b128 v[32:35], v149 offset:23040
	s_waitcnt lgkmcnt(2)
	v_mfma_f32_32x32x16_bf16 v[48:63], v[36:39], v[112:115], v[48:63]
	v_add_f32_e32 v36, v168, v40
	v_add_f32_e32 v36, v169, v36
	v_add_f32_e32 v36, v170, v36
	v_add_f32_e32 v36, v171, v36
	v_add_f32_e32 v36, v172, v36
	v_add_f32_e32 v132, v173, v36
	v_add_f32_e32 v132, v174, v132
	s_waitcnt lgkmcnt(0)
	v_mfma_f32_32x32x16_bf16 v[32:47], v[32:35], v[124:127], 0
	v_add_f32_e32 v132, v175, v132
	v_add_f32_e32 v132, v177, v132
	v_add_f32_e32 v132, v178, v132
	v_add_f32_e32 v132, v179, v132
	v_add_f32_e32 v136, v180, v132
	ds_read_b128 v[132:135], v149 offset:23104
	v_mfma_f32_32x32x16_bf16 v[32:47], v[128:131], v[120:123], v[32:47]
	v_add_f32_e32 v128, v181, v136
	v_add_f32_e32 v128, v182, v128
	v_add_f32_e32 v128, v183, v128
	v_add_f32_e32 v128, v184, v128
	v_add_f32_e32 v128, v185, v128
	v_add_f32_e32 v136, v186, v128
	ds_read_b128 v[128:131], v149 offset:23136
	s_waitcnt lgkmcnt(1)
	v_mfma_f32_32x32x16_bf16 v[32:47], v[132:135], v[116:119], v[32:47]
	v_add_f32_e32 v132, v187, v136
	v_add_f32_e32 v132, v188, v132
	v_add_f32_e32 v132, v189, v132
	v_add_f32_e32 v168, v190, v132
	v_mov_b32_e32 v169, v168
	s_nop 1
	v_permlane32_swap_b32_e32 v168, v169
	s_waitcnt lgkmcnt(0)
	v_mfma_f32_32x32x16_bf16 v[32:47], v[128:131], v[112:115], v[32:47]
	v_max3_f32 v128, v48, s6, v49
	v_max3_f32 v128, v128, v50, v51
	v_max3_f32 v128, v128, v52, v53
	v_max3_f32 v128, v128, v54, v55
	v_max3_f32 v128, v128, v56, v57
	v_max3_f32 v128, v128, v58, v59
	v_max3_f32 v128, v128, v60, v61
	v_max3_f32 v128, v128, v62, v63
	s_nop 3
	v_max3_f32 v128, v128, v32, v33
	v_max3_f32 v128, v128, v34, v35
	v_max3_f32 v128, v128, v36, v37
	v_max3_f32 v128, v128, v38, v39
	v_max3_f32 v128, v128, v40, v41
	v_max3_f32 v128, v128, v42, v43
	v_max3_f32 v128, v128, v44, v45
	v_max3_f32 v128, v128, v46, v47
	v_mul_f32_e32 v128, 0x3e38aa3b, v128
	v_mov_b32_e32 v129, v128
	s_nop 1
	v_permlane32_swap_b32_e32 v128, v129
	v_max3_f32 v128, v155, v128, v129
	v_cmp_lt_f32_e32 vcc, s7, v128
	v_sub_f32_e32 v158, v155, v128
	v_exp_f32_e32 v158, v158
	v_cndmask_b32_e64 v170, v163, -v128, vcc
	v_fmamk_f32 v48, v48, 0x3e38aa3b, v170
	v_exp_f32_e32 v129, v48
	v_fmamk_f32 v48, v49, 0x3e38aa3b, v170
	v_exp_f32_e32 v130, v48
	v_fmamk_f32 v48, v50, 0x3e38aa3b, v170
	v_exp_f32_e32 v131, v48
	v_fmamk_f32 v48, v51, 0x3e38aa3b, v170
	v_exp_f32_e32 v132, v48
	v_fmamk_f32 v49, v52, 0x3e38aa3b, v170
	v_add_f32_e32 v48, 0, v129
	v_exp_f32_e32 v133, v49
	v_fmamk_f32 v49, v53, 0x3e38aa3b, v170
	v_add_f32_e32 v48, v130, v48
	v_exp_f32_e32 v134, v49
	v_fmamk_f32 v49, v54, 0x3e38aa3b, v170
	v_add_f32_e32 v48, v131, v48
	v_exp_f32_e32 v135, v49
	v_fmamk_f32 v49, v55, 0x3e38aa3b, v170
	v_add_f32_e32 v48, v132, v48
	v_exp_f32_e32 v136, v49
	v_fmamk_f32 v49, v56, 0x3e38aa3b, v170
	v_add_f32_e32 v48, v133, v48
	v_exp_f32_e32 v49, v49
	v_fmamk_f32 v50, v57, 0x3e38aa3b, v170
; #define MFMA32(a, b, c) __builtin_amdgcn_mfma_f32_32x32x16_bf16((a), (b), (c), 0, 0, 0)
; DI void pv_tile(const u16* Vs, const f32x16* s, f32x16* o, int rl, int hh) {
; #pragma unroll
;   for (int kk = 0; kk < 4; ++kk) {
;     const int kb = kk >> 1, i0 = 8 * (kk & 1);
;     bf16x8 pf = pack8(s[kb][i0], s[kb][i0 + 1], s[kb][i0 + 2], s[kb][i0 + 3], s[kb][i0 + 4], s[kb][i0 + 5], s[kb][i0 + 6], s[kb][i0 + 7]);
; #pragma unroll
;     for (int db = 0; db < 2; ++db) {
;       const u16* vp = Vs + (db * 32 + rl) * KVS + kk * 16 + hh * 4;
;       s16x4 lo = *(const s16x4*)vp, hi = *(const s16x4*)(vp + 8);
;       bf16x8 a = __builtin_shufflevector(lo, hi, 0, 1, 2, 3, 4, 5, 6, 7);
;       o[db] = MFMA32(a, pf, o[db]);
;     }
;   }
; }
; DI void moba_gather_phase(int ws, PP p, char* shm) {
;     ...
;       if (st == 1) {
;         have_qn = itn < total;
;         if (have_qn) {
;           const int bhn = lin >> 5;
;           load_qf(qfn, u + ((long)(bhn >> 3) * SEQ + (int)(entn >> 2)) * IN0 + 1024 + (bhn & 7) * 64, hh);
;         }
;       }
	v_add_f32_e32 v48, v134, v48
	v_exp_f32_e32 v51, v50
	v_fmamk_f32 v50, v58, 0x3e38aa3b, v170
	v_add_f32_e32 v48, v135, v48
	v_exp_f32_e32 v53, v50
	v_fmamk_f32 v50, v59, 0x3e38aa3b, v170
	v_add_f32_e32 v48, v136, v48
	v_exp_f32_e32 v55, v50
	v_fmamk_f32 v50, v60, 0x3e38aa3b, v170
	v_add_f32_e32 v48, v49, v48
	v_exp_f32_e32 v57, v50
	v_fmamk_f32 v50, v61, 0x3e38aa3b, v170
	v_add_f32_e32 v48, v51, v48
	v_exp_f32_e32 v59, v50
	v_fmamk_f32 v50, v62, 0x3e38aa3b, v170
	v_add_f32_e32 v48, v53, v48
	v_exp_f32_e32 v61, v50
	v_fmamk_f32 v50, v63, 0x3e38aa3b, v170
	v_add_f32_e32 v48, v55, v48
	v_exp_f32_e32 v62, v50
	v_add_f32_e32 v48, v57, v48
	v_add_f32_e32 v48, v59, v48
	v_add_f32_e32 v48, v61, v48
	v_fmamk_f32 v32, v32, 0x3e38aa3b, v170
	v_add_f32_e32 v56, v62, v48
	v_exp_f32_e32 v48, v32
	v_fmamk_f32 v32, v33, 0x3e38aa3b, v170
	v_exp_f32_e32 v50, v32
	v_fmamk_f32 v32, v34, 0x3e38aa3b, v170
	v_exp_f32_e32 v52, v32
	v_fmamk_f32 v32, v35, 0x3e38aa3b, v170
	v_exp_f32_e32 v54, v32
	v_fmamk_f32 v33, v36, 0x3e38aa3b, v170
	v_add_f32_e32 v32, v48, v56
	v_exp_f32_e32 v56, v33
	v_fmamk_f32 v33, v37, 0x3e38aa3b, v170
	v_add_f32_e32 v32, v50, v32
	v_exp_f32_e32 v58, v33
	v_fmamk_f32 v33, v38, 0x3e38aa3b, v170
	v_add_f32_e32 v32, v52, v32
	v_exp_f32_e32 v60, v33
	v_fmamk_f32 v33, v39, 0x3e38aa3b, v170
	v_add_f32_e32 v32, v54, v32
	v_exp_f32_e32 v39, v33
	v_add_f32_e32 v32, v56, v32
	v_add_f32_e32 v32, v58, v32
	v_add_f32_e32 v32, v60, v32
	v_add_f32_e32 v36, v39, v32
	v_fmamk_f32 v32, v40, 0x3e38aa3b, v170
	v_exp_f32_e32 v32, v32
	v_fmamk_f32 v33, v41, 0x3e38aa3b, v170
	v_exp_f32_e32 v33, v33
	v_fmamk_f32 v34, v42, 0x3e38aa3b, v170
	v_exp_f32_e32 v34, v34
	v_fmamk_f32 v35, v43, 0x3e38aa3b, v170
	v_exp_f32_e32 v35, v35
	v_add_f32_e32 v36, v32, v36
	v_add_f32_e32 v36, v33, v36
	v_add_f32_e32 v36, v34, v36
	v_add_f32_e32 v41, v35, v36
	v_fmamk_f32 v36, v44, 0x3e38aa3b, v170
	v_exp_f32_e32 v36, v36
	v_fmamk_f32 v37, v45, 0x3e38aa3b, v170
	v_exp_f32_e32 v37, v37
	v_fmamk_f32 v38, v46, 0x3e38aa3b, v170
	v_exp_f32_e32 v38, v38
	v_fmac_f32_e32 v170, 0x3e38aa3b, v47
	v_exp_f32_e32 v40, v170
	v_add_f32_e32 v41, v36, v41
	v_add_f32_e32 v41, v37, v41
	v_add_f32_e32 v41, v38, v41
	v_add_f32_e32 v170, v40, v41
	v_mov_b32_e32 v171, v170
	s_nop 1
	v_permlane32_swap_b32_e32 v170, v171
	v_cmp_gt_f32_e32 vcc, v128, v155
	s_cbranch_vccz .LBB0_746
	v_pk_mul_f32 v[14:15], v[14:15], v[158:159] op_sel_hi:[1,0]
	v_pk_mul_f32 v[12:13], v[12:13], v[158:159] op_sel_hi:[1,0]
	v_pk_mul_f32 v[10:11], v[10:11], v[158:159] op_sel_hi:[1,0]
	v_pk_mul_f32 v[8:9], v[8:9], v[158:159] op_sel_hi:[1,0]
	v_pk_mul_f32 v[6:7], v[6:7], v[158:159] op_sel_hi:[1,0]
	v_pk_mul_f32 v[4:5], v[4:5], v[158:159] op_sel_hi:[1,0]
	v_pk_mul_f32 v[2:3], v[2:3], v[158:159] op_sel_hi:[1,0]
	v_pk_mul_f32 v[0:1], v[0:1], v[158:159] op_sel_hi:[1,0]
	v_pk_mul_f32 v[30:31], v[30:31], v[158:159] op_sel_hi:[1,0]
	v_pk_mul_f32 v[28:29], v[28:29], v[158:159] op_sel_hi:[1,0]
	v_pk_mul_f32 v[26:27], v[26:27], v[158:159] op_sel_hi:[1,0]
	v_pk_mul_f32 v[24:25], v[24:25], v[158:159] op_sel_hi:[1,0]
	v_pk_mul_f32 v[22:23], v[22:23], v[158:159] op_sel_hi:[1,0]
	v_pk_mul_f32 v[20:21], v[20:21], v[158:159] op_sel_hi:[1,0]
	v_pk_mul_f32 v[18:19], v[18:19], v[158:159] op_sel_hi:[1,0]
	v_pk_mul_f32 v[16:17], v[16:17], v[158:159] op_sel_hi:[1,0]
.LBB0_746:
	v_add_u32_e32 v41, 0x6800, v161
	v_cvt_pk_bf16_f32 v42, v129, v130
	v_cvt_pk_bf16_f32 v43, v131, v132
	v_cvt_pk_bf16_f32 v44, v133, v134
	v_cvt_pk_bf16_f32 v45, v135, v136
	s_nop 1
	ds_read2_b64 v[130:133], v41 offset0:128 offset1:130
	v_add_u32_e32 v63, 0x7800, v161
	s_andn2_b64 vcc, exec, s[16:17]
	s_waitcnt lgkmcnt(0)
	v_mfma_f32_32x32x16_bf16 v[16:31], v[130:133], v[42:45], v[16:31]
	ds_read2_b64 v[130:133], v63 offset0:192 offset1:194
	s_waitcnt lgkmcnt(0)
	v_mfma_f32_32x32x16_bf16 v[0:15], v[130:133], v[42:45], v[0:15]
	v_cvt_pk_bf16_f32 v42, v49, v51
	v_cvt_pk_bf16_f32 v43, v53, v55
	v_cvt_pk_bf16_f32 v44, v57, v59
	v_cvt_pk_bf16_f32 v45, v61, v62
	s_nop 1
	ds_read2_b64 v[130:133], v41 offset0:132 offset1:134
	s_waitcnt lgkmcnt(0)
	v_mfma_f32_32x32x16_bf16 v[16:31], v[130:133], v[42:45], v[16:31]
	ds_read2_b64 v[130:133], v63 offset0:196 offset1:198
	s_waitcnt lgkmcnt(0)
	v_mfma_f32_32x32x16_bf16 v[0:15], v[130:133], v[42:45], v[0:15]
	v_cvt_pk_bf16_f32 v42, v48, v50
	v_cvt_pk_bf16_f32 v43, v52, v54
	v_cvt_pk_bf16_f32 v44, v56, v58
	v_cvt_pk_bf16_f32 v45, v60, v39
	s_nop 1
	ds_read2_b64 v[46:49], v41 offset0:136 offset1:138
	s_waitcnt lgkmcnt(0)
	v_mfma_f32_32x32x16_bf16 v[16:31], v[46:49], v[42:45], v[16:31]
	ds_read2_b64 v[46:49], v63 offset0:200 offset1:202
	s_waitcnt lgkmcnt(0)
	v_mfma_f32_32x32x16_bf16 v[0:15], v[46:49], v[42:45], v[0:15]
	v_cvt_pk_bf16_f32 v42, v32, v33
	v_cvt_pk_bf16_f32 v43, v34, v35
	v_cvt_pk_bf16_f32 v44, v36, v37
	v_cvt_pk_bf16_f32 v45, v38, v40
	s_nop 1
	ds_read2_b64 v[32:35], v41 offset0:140 offset1:142
	s_waitcnt lgkmcnt(0)
	v_mfma_f32_32x32x16_bf16 v[16:31], v[32:35], v[42:45], v[16:31]
	ds_read2_b64 v[32:35], v63 offset0:204 offset1:206
	s_waitcnt lgkmcnt(0)
	v_mfma_f32_32x32x16_bf16 v[0:15], v[32:35], v[42:45], v[0:15]
	s_cbranch_vccnz .LBB0_748
	s_ashr_i32 s4, s34, 8
	s_ashr_i32 s5, s4, 31
	s_lshl_b64 s[4:5], s[4:5], 13
	s_waitcnt vmcnt(0)
	v_lshrrev_b32_e32 v136, 2, v151
	v_lshl_add_u64 v[32:33], s[4:5], 0, v[136:137]
	v_mov_b64_e32 v[34:35], s[24:25]
	v_mad_u64_u32 v[34:35], s[4:5], v32, s0, v[34:35]
	s_lshl_b32 s4, s34, 2
	v_mad_i32_i24 v35, v33, s0, v35
	s_and_b32 s38, s4, 0x380
	v_lshl_add_u64 v[32:33], v[34:35], 0, s[38:39]
	v_mov_b32_e32 v155, v137
	v_lshl_add_u64 v[32:33], v[32:33], 0, v[154:155]
	global_load_dwordx4 v[64:67], v[32:33], off offset:2048
	global_load_dwordx4 v[68:71], v[32:33], off offset:2080
	global_load_dwordx4 v[72:75], v[32:33], off offset:2112
	global_load_dwordx4 v[76:79], v[32:33], off offset:2144

; #define MFMA32(a, b, c) __builtin_amdgcn_mfma_f32_32x32x16_bf16((a), (b), (c), 0, 0, 0)
; DI void qk_tile(const u16* Ks, const bf16x8* qf, f32x16* s, int rl, int hh) {
; #pragma unroll
;   for (int kb = 0; kb < 2; ++kb) {
; #pragma unroll
;     for (int i = 0; i < 16; ++i) s[kb][i] = 0.f;
; #pragma unroll
;     for (int ks = 0; ks < 4; ++ks) {
;       bf16x8 a = *(const bf16x8*)(Ks + (kb * 32 + rl) * KVS + ks * 16 + hh * 8);
;       s[kb] = MFMA32(a, qf[ks], s[kb]);
;     }
;   }
; }
; template <class TF, class BODY>
; DI void kv_loop(u16* kvb, int ntiles, int tid, TF tf, BODY body) {
;     ...
;   for (int i = 0; i < ntiles; ++i) {
;     const int cur = i & 1;
;     if (i + 1 < ntiles) {
;       tf(i + 1, kp, ldk, vp, ldv);
;       kv_issue(r, kp, ldk, vp, ldv, tid);
;     }
;     body(i, kvb + cur * 2 * KVT, kvb + cur * 2 * KVT + KVT);
;     if (i + 1 < ntiles) kv_write(r, kvb + (cur ^ 1) * 2 * KVT, kvb + (cur ^ 1) * 2 * KVT + KVT, tid);
.LBB0_1778:
	s_or_b64 exec, exec, s[12:13]
	v_cmp_ne_u32_e64 s[10:11], 0, v128
	s_and_b32 s19, s5, 1
	s_mov_b64 vcc, s[10:11]
	s_cbranch_vccz .LBB0_1791
	s_mul_i32 s12, s19, 0x4800
	v_or_b32_e32 v202, s12, v0
	v_lshl_add_u32 v129, v246, 1, v202
	ds_read_b128 v[112:115], v129
	ds_read_b128 v[116:119], v129 offset:32
	v_cmp_eq_u32_e32 vcc, -1, v128
	v_cmp_eq_u32_e64 s[12:13], 0, v128
	s_cmp_lg_u64 vcc, -1
	s_waitcnt vmcnt(2) lgkmcnt(1)
	v_mfma_f32_32x32x16_bf16 v[144:159], v[112:115], v[2:5], 0
	s_waitcnt lgkmcnt(0)
	v_mfma_f32_32x32x16_bf16 v[144:159], v[116:119], v[176:179], v[144:159]
	ds_read_b128 v[112:115], v129 offset:64
	ds_read_b128 v[116:119], v129 offset:96
	s_waitcnt lgkmcnt(1)
	v_mfma_f32_32x32x16_bf16 v[144:159], v[112:115], v[180:183], v[144:159]
	ds_read_b128 v[112:115], v129 offset:4608
	ds_read_b128 v[130:133], v129 offset:4640
	s_waitcnt lgkmcnt(2)
	v_mfma_f32_32x32x16_bf16 v[144:159], v[116:119], v[184:187], v[144:159]
	s_waitcnt lgkmcnt(1)
	v_mfma_f32_32x32x16_bf16 v[112:127], v[112:115], v[2:5], 0
	s_waitcnt lgkmcnt(0)
	v_mfma_f32_32x32x16_bf16 v[112:127], v[130:133], v[176:179], v[112:127]
	ds_read_b128 v[130:133], v129 offset:4672
	ds_read_b128 v[134:137], v129 offset:4704
	s_waitcnt lgkmcnt(1)
	v_mfma_f32_32x32x16_bf16 v[112:127], v[130:133], v[180:183], v[112:127]
	s_waitcnt lgkmcnt(0)
	v_mfma_f32_32x32x16_bf16 v[112:127], v[134:137], v[184:187], v[112:127]
	s_cbranch_scc0 .LBB0_1792
	s_or_b64 s[12:13], s[12:13], vcc
	s_cmp_lg_u64 s[12:13], -1
	s_cbranch_scc0 .LBB0_1793
	v_and_b32_e32 v129, 1, v128
	v_cmp_eq_u32_e32 vcc, 1, v129
	v_and_b32_e32 v130, 2, v128
	v_and_b32_e32 v132, 4, v128
	v_cndmask_b32_e32 v129, v204, v144, vcc
	v_cmp_ne_u32_e32 vcc, 0, v130
	v_and_b32_e32 v133, 8, v128
	v_and_b32_e32 v134, 16, v128
	v_cndmask_b32_e32 v130, v204, v145, vcc
	v_cmp_ne_u32_e32 vcc, 0, v132
	v_and_b32_e32 v135, 32, v128
	v_and_b32_e32 v136, 64, v128
	v_cndmask_b32_e32 v132, v204, v146, vcc
	v_cmp_ne_u32_e32 vcc, 0, v133
	v_and_b32_e32 v137, 0x80, v128
	v_and_b32_e32 v138, 0x100, v128
	v_cndmask_b32_e32 v133, v204, v147, vcc
	v_cmp_ne_u32_e32 vcc, 0, v134
	v_and_b32_e32 v139, 0x200, v128
	v_and_b32_e32 v140, 0x400, v128
	v_cndmask_b32_e32 v134, v204, v148, vcc
	v_cmp_ne_u32_e32 vcc, 0, v135
	v_and_b32_e32 v141, 0x800, v128
	v_and_b32_e32 v142, 0x1000, v128
	v_cndmask_b32_e32 v135, v204, v149, vcc
	v_cmp_ne_u32_e32 vcc, 0, v136
	v_and_b32_e32 v143, 0x2000, v128
	v_and_b32_e32 v160, 0x4000, v128
	v_cndmask_b32_e32 v136, v204, v150, vcc
	v_cmp_ne_u32_e32 vcc, 0, v137
	v_and_b32_e32 v161, 0x8000, v128
	v_and_b32_e32 v162, 0x10000, v128
	v_cndmask_b32_e32 v137, v204, v151, vcc
	v_cmp_ne_u32_e32 vcc, 0, v138
	v_and_b32_e32 v163, 0x20000, v128
	v_and_b32_e32 v164, 0x40000, v128
	v_cndmask_b32_e32 v138, v204, v152, vcc
	v_cmp_ne_u32_e32 vcc, 0, v139
	v_max3_f32 v131, v129, s77, v130
	v_and_b32_e32 v165, 0x80000, v128
	v_cndmask_b32_e32 v139, v204, v153, vcc
	v_cmp_ne_u32_e32 vcc, 0, v140
	v_max3_f32 v131, v131, v132, v133
	v_and_b32_e32 v166, 0x100000, v128
	v_cndmask_b32_e32 v140, v204, v154, vcc
	v_cmp_ne_u32_e32 vcc, 0, v141
	v_max3_f32 v131, v131, v134, v135
	v_and_b32_e32 v167, 0x200000, v128
	v_cndmask_b32_e32 v141, v204, v155, vcc
	v_cmp_ne_u32_e32 vcc, 0, v142
	v_max3_f32 v131, v131, v136, v137
	v_and_b32_e32 v168, 0x400000, v128
	v_cndmask_b32_e32 v142, v204, v156, vcc
	v_cmp_ne_u32_e32 vcc, 0, v143
	v_max3_f32 v131, v131, v138, v139
	v_and_b32_e32 v169, 0x800000, v128
	v_cndmask_b32_e32 v143, v204, v157, vcc
	v_cmp_ne_u32_e32 vcc, 0, v160
	v_max3_f32 v131, v131, v140, v141
	v_and_b32_e32 v170, 0x1000000, v128
	v_cndmask_b32_e32 v160, v204, v158, vcc
	v_cmp_ne_u32_e32 vcc, 0, v161
	v_max3_f32 v131, v131, v142, v143
	v_and_b32_e32 v171, 0x2000000, v128
	v_cndmask_b32_e32 v161, v204, v159, vcc
	v_cmp_ne_u32_e32 vcc, 0, v162
	v_max3_f32 v131, v131, v160, v161
	v_and_b32_e32 v172, 0x4000000, v128
	v_cndmask_b32_e32 v162, v204, v112, vcc
	v_cmp_ne_u32_e32 vcc, 0, v163
	v_and_b32_e32 v173, 0x8000000, v128
	v_and_b32_e32 v174, 0x10000000, v128
	v_cndmask_b32_e32 v163, v204, v113, vcc
	v_cmp_ne_u32_e32 vcc, 0, v164
	v_max3_f32 v131, v131, v162, v163
	v_and_b32_e32 v175, 0x20000000, v128
	v_cndmask_b32_e32 v164, v204, v114, vcc
	v_cmp_ne_u32_e32 vcc, 0, v165
	v_and_b32_e32 v198, 2.0, v128
	s_nop 0
	v_cndmask_b32_e32 v165, v204, v115, vcc
	v_cmp_ne_u32_e32 vcc, 0, v166
	v_max3_f32 v131, v131, v164, v165
	s_nop 0
	v_cndmask_b32_e32 v166, v204, v116, vcc
	v_cmp_ne_u32_e32 vcc, 0, v167
	s_nop 1
	v_cndmask_b32_e32 v167, v204, v117, vcc
	v_cmp_ne_u32_e32 vcc, 0, v168
	v_max3_f32 v131, v131, v166, v167
	s_nop 0
	v_cndmask_b32_e32 v168, v204, v118, vcc
; DI float fexp2(float x) { return __builtin_amdgcn_exp2f(x); }
; template <int MODE>
; DI void osm(f32x16* s, uint32_t vm, float& m, float& l, f32x16* o) {
;   float mx = -1e30f;
; #pragma unroll
;   for (int kb = 0; kb < 2; ++kb)
; #pragma unroll
;     for (int i = 0; i < 16; ++i) {
;       if (MODE == 2) s[kb][i] = ((vm >> (kb * 16 + i)) & 1u) ? s[kb][i] : -1e30f;
;       mx = fmaxf(mx, s[kb][i]);
;     }
;   mx *= SCL2;
;   if (MODE == 1) mx = vm ? mx : -1e30f;
;   mx = xmax32(mx);
;   const float mn = fmaxf(m, mx);
;   const float alpha = fexp2(m - mn);
;   const bool rowok = (MODE == 1) ? (vm != 0u) : true;
;   const float mu = (rowok && mn > -1e29f) ? mn : 1e30f;
;   float rs = 0.f;
; #pragma unroll
;   for (int kb = 0; kb < 2; ++kb)
; #pragma unroll
;     for (int i = 0; i < 16; ++i) {
;       const float pv = fexp2(__builtin_fmaf(s[kb][i], SCL2, -mu));
;       s[kb][i] = pv;
;       rs += pv;
;     }
;   rs = xsum32(rs);
;   l = l * alpha + rs;
;   if (__ballot(mn > m) != 0ull) {
; #pragma unroll
;     for (int db = 0; db < 2; ++db)
; #pragma unroll
;       for (int i = 0; i < 16; ++i) o[db][i] *= alpha;
;   }
;   m = mn;
; }
	v_cmp_ne_u32_e32 vcc, 0, v169
	s_nop 1
	v_cndmask_b32_e32 v169, v204, v119, vcc
	v_cmp_ne_u32_e32 vcc, 0, v170
	v_max3_f32 v131, v131, v168, v169
	s_nop 0
	v_cndmask_b32_e32 v170, v204, v120, vcc
	v_cmp_ne_u32_e32 vcc, 0, v171
	s_nop 1
	v_cndmask_b32_e32 v171, v204, v121, vcc
	v_cmp_ne_u32_e32 vcc, 0, v172
	v_max3_f32 v131, v131, v170, v171
	s_nop 0
	v_cndmask_b32_e32 v172, v204, v122, vcc
	v_cmp_ne_u32_e32 vcc, 0, v173
	s_nop 1
	v_cndmask_b32_e32 v173, v204, v123, vcc
	v_cmp_ne_u32_e32 vcc, 0, v174
	v_max3_f32 v131, v131, v172, v173
	s_nop 0
	v_cndmask_b32_e32 v174, v204, v124, vcc
	v_cmp_ne_u32_e32 vcc, 0, v175
	s_nop 1
	v_cndmask_b32_e32 v175, v204, v125, vcc
	v_cmp_ne_u32_e32 vcc, 0, v198
	v_max3_f32 v131, v131, v174, v175
	s_nop 0
	v_cndmask_b32_e32 v198, v204, v126, vcc
	v_cmp_gt_i32_e32 vcc, 0, v128
	s_nop 1
	v_cndmask_b32_e32 v229, v204, v127, vcc
	v_max3_f32 v128, v131, v198, v229
	v_mul_f32_e32 v128, 0x3e38aa3b, v128
	v_mov_b32_e32 v131, v128
	s_nop 1
	v_permlane32_swap_b32_e32 v128, v131
	v_max3_f32 v249, v201, v128, v131
	v_cmp_lt_f32_e32 vcc, s1, v249
	v_sub_f32_e32 v250, v201, v249
	s_nop 0
	v_cndmask_b32_e64 v251, v204, -v249, vcc
	v_fmamk_f32 v128, v129, 0x3e38aa3b, v251
	v_exp_f32_e32 v128, v128
	v_fmamk_f32 v129, v130, 0x3e38aa3b, v251
	v_exp_f32_e32 v129, v129
	v_fmamk_f32 v130, v132, 0x3e38aa3b, v251
	v_exp_f32_e32 v130, v130
	v_fmamk_f32 v131, v133, 0x3e38aa3b, v251
	v_exp_f32_e32 v131, v131
	v_add_f32_e32 v132, 0, v128
	v_add_f32_e32 v132, v129, v132
	v_add_f32_e32 v132, v130, v132
	v_add_f32_e32 v252, v131, v132
	v_fmamk_f32 v132, v134, 0x3e38aa3b, v251
	v_exp_f32_e32 v132, v132
	v_fmamk_f32 v133, v135, 0x3e38aa3b, v251
	v_exp_f32_e32 v133, v133
	v_fmamk_f32 v134, v136, 0x3e38aa3b, v251
	v_exp_f32_e32 v134, v134
	v_fmamk_f32 v135, v137, 0x3e38aa3b, v251
	v_exp_f32_e32 v135, v135
	v_add_f32_e32 v136, v132, v252
	v_add_f32_e32 v136, v133, v136
	v_add_f32_e32 v136, v134, v136
	v_add_f32_e32 v252, v135, v136
	v_fmamk_f32 v136, v138, 0x3e38aa3b, v251
	v_exp_f32_e32 v136, v136
	v_fmamk_f32 v137, v139, 0x3e38aa3b, v251
	v_exp_f32_e32 v137, v137
	v_fmamk_f32 v138, v140, 0x3e38aa3b, v251
	v_exp_f32_e32 v138, v138
	v_fmamk_f32 v139, v141, 0x3e38aa3b, v251
	v_exp_f32_e32 v139, v139
	v_add_f32_e32 v140, v136, v252
	v_add_f32_e32 v140, v137, v140
	v_add_f32_e32 v140, v138, v140
	v_add_f32_e32 v252, v139, v140
	v_fmamk_f32 v140, v142, 0x3e38aa3b, v251
	v_exp_f32_e32 v140, v140
	v_fmamk_f32 v141, v143, 0x3e38aa3b, v251
	v_exp_f32_e32 v141, v141
	v_fmamk_f32 v142, v160, 0x3e38aa3b, v251
	v_exp_f32_e32 v142, v142
	v_fmamk_f32 v143, v161, 0x3e38aa3b, v251
	v_exp_f32_e32 v143, v143
	v_add_f32_e32 v160, v140, v252
	v_add_f32_e32 v160, v141, v160
	v_add_f32_e32 v160, v142, v160
	v_add_f32_e32 v252, v143, v160
	v_fmamk_f32 v160, v162, 0x3e38aa3b, v251
	v_exp_f32_e32 v160, v160
	v_fmamk_f32 v161, v163, 0x3e38aa3b, v251
	v_exp_f32_e32 v161, v161
	v_fmamk_f32 v162, v164, 0x3e38aa3b, v251
	v_exp_f32_e32 v162, v162
	v_fmamk_f32 v163, v165, 0x3e38aa3b, v251
	v_exp_f32_e32 v163, v163
	v_add_f32_e32 v164, v160, v252
	v_add_f32_e32 v164, v161, v164
	v_add_f32_e32 v164, v162, v164
	v_add_f32_e32 v252, v163, v164
	v_fmamk_f32 v164, v166, 0x3e38aa3b, v251
	v_exp_f32_e32 v164, v164
	v_fmamk_f32 v165, v167, 0x3e38aa3b, v251
	v_exp_f32_e32 v165, v165
	v_fmamk_f32 v166, v168, 0x3e38aa3b, v251
	v_exp_f32_e32 v166, v166
	v_fmamk_f32 v167, v169, 0x3e38aa3b, v251
	v_exp_f32_e32 v167, v167
	v_add_f32_e32 v168, v164, v252
	v_add_f32_e32 v168, v165, v168
	v_add_f32_e32 v168, v166, v168
	v_add_f32_e32 v252, v167, v168
	v_fmamk_f32 v168, v170, 0x3e38aa3b, v251
	v_exp_f32_e32 v168, v168
	v_fmamk_f32 v169, v171, 0x3e38aa3b, v251
	v_exp_f32_e32 v169, v169
	v_fmamk_f32 v170, v172, 0x3e38aa3b, v251
	v_exp_f32_e32 v170, v170
	v_fmamk_f32 v171, v173, 0x3e38aa3b, v251
	v_exp_f32_e32 v171, v171
	v_add_f32_e32 v172, v168, v252
	v_add_f32_e32 v172, v169, v172
	v_add_f32_e32 v172, v170, v172
	v_add_f32_e32 v252, v171, v172
	v_fmamk_f32 v172, v174, 0x3e38aa3b, v251
	v_exp_f32_e32 v172, v172
	v_fmamk_f32 v173, v175, 0x3e38aa3b, v251
	v_exp_f32_e32 v173, v173
	v_fmamk_f32 v174, v198, 0x3e38aa3b, v251
	v_exp_f32_e32 v174, v174
	v_fmac_f32_e32 v251, 0x3e38aa3b, v229
	v_exp_f32_e32 v175, v251
	v_add_f32_e32 v198, v172, v252
	v_add_f32_e32 v198, v173, v198
	v_add_f32_e32 v198, v174, v198
	v_add_f32_e32 v229, v175, v198
	v_exp_f32_e32 v198, v250
	v_mov_b32_e32 v250, v229
	s_nop 1
	v_permlane32_swap_b32_e32 v229, v250
	v_cmp_gt_f32_e32 vcc, v249, v201
	v_add_f32_e32 v250, v229, v250
	s_cmp_lg_u64 vcc, 0
	v_fmac_f32_e32 v250, v200, v198
	s_cselect_b64 s[12:13], -1, 0
	s_cbranch_execnz .LBB0_1783
